# GU SwiGLU epilogue: next-unit row-stat loads kept in flight during activation math (wait moved to consumer)
# speedup vs baseline: 1.0126x; 1.0126x over previous
; DI u32x4 pk8(f32x4 a, f32x4 b) { u32x4 o; o.x = pk2(a.x, a.y); o.y = pk2(a.z, a.w); o.z = pk2(b.x, b.y); o.w = pk2(b.z, b.w); return o; }
; DI float fexp2(float x) { return __builtin_amdgcn_exp2f(x); }
; DI float frcp(float x) { return __builtin_amdgcn_rcpf(x); }
; #define EPI_SCHED() __builtin_amdgcn_sched_barrier(0)
;     DI static void unpark(float (&rs)[2][4], int t) { const LAS f32x4* p = slot(t); const f32x4 a = p[0], b = p[1]; rs[0][0] = a.x; rs[0][1] = a.y; rs[0][2] = a.z; rs[0][3] = a.w; rs[1][0] = b.x; rs[1][1] = b.y; rs[1][2] = b.z; rs[1][3] = b.w; }
;     DI void operator()(const AccT& acc, const Unit& u, const Unit& nxt, bool has_next, int wr, int wc, int fr, int fq, float (&rs_unused)[2][4]) const {
;         const size_t row0 = (size_t)u.pm * 256 + wr * 64 + fr;
;         const int myt = (wr * 4 + wc) * 64 + fq * 16 + fr;
;         float rs[2][4]; unpark(rs, myt);
;         f32x4 nv[2][4];
;         if (has_next) {
;             const size_t nrow0 = (size_t)nxt.pm * 256 + wr * 64 + fr;
; #pragma unroll
;             for (int ai = 0; ai < 2; ++ai)
; #pragma unroll
;                 for (int m = 0; m < 4; ++m) nv[ai][m] = *(const f32x4*)(ss + (nrow0 + ai * 128 + m * 16) * 16 + 4 * fq);
;         }
; #pragma unroll
;         for (int ai = 0; ai < 2; ++ai)
; #pragma unroll
;             for (int m = 0; m < 4; ++m) {
;                 EPI_SCHED(); const size_t row = row0 + ai * 128 + m * 16;
;                 f32x4 o[2];
;                 const float c1 = -LOG2E * rs[ai][m], rs2 = rs[ai][m] * rs[ai][m];
; #pragma unroll
;                 for (int n = 0; n < 2; ++n) {
;                     const f32x4 gt = acc[ai][0][m][n], t = gt * acc[ai][1][m][n];
; #pragma unroll
;                     for (int e = 0; e < 4; ++e) o[n][e] = t[e] * (rs2 * frcp(1.f + fexp2(gt[e] * c1)));
;                 }
;                 *(u32x4*)(hid + row * FF + u.pn * 128 + wc * 32 + fq * 8) = pk8(o[0], o[1]);
.LBB0_1820:
	s_mov_b32 s1, -1
	s_andn2_b64 vcc, exec, s[24:25]
	v_mbcnt_lo_u32_b32 v98, s1, 0
	v_mbcnt_hi_u32_b32 v98, s1, v98
	s_add_i32 s1, 0, 0x20010
	v_and_b32_e32 v179, 15, v98
	v_ashrrev_i32_e32 v178, 4, v98
	v_or_b32_e32 v98, s45, v179
	v_lshlrev_b32_e32 v98, 5, v98
	v_lshl_add_u32 v99, v178, 9, s1
	v_add_u32_e32 v177, v99, v98
	ds_read_b128 v[150:153], v177
	ds_read_b128 v[146:149], v177 offset:16
	v_cndmask_b32_e64 v98, 0, 1, s[24:25]
	v_cmp_ne_u32_e64 s[2:3], 1, v98
	s_cbranch_vccnz .LBB0_1822
	s_lshl_b64 s[24:25], s[14:15], 8
	s_add_u32 s1, s24, s39
	s_addc_u32 s15, s25, s44
	v_lshlrev_b32_e32 v100, 2, v178
	v_mov_b32_e32 v99, s15
	v_or_b32_e32 v98, s1, v179
	v_ashrrev_i32_e32 v101, 31, v100
	v_lshl_add_u64 v[100:101], v[100:101], 2, s[4:5]
	v_lshlrev_b64 v[98:99], 6, v[98:99]
	v_lshl_add_u64 v[98:99], v[100:101], 0, v[98:99]
	s_movk_i32 s1, 0x2000
	global_load_dwordx4 v[154:157], v[98:99], off
	global_load_dwordx4 v[142:145], v[98:99], off offset:1024
	global_load_dwordx4 v[166:169], v[98:99], off offset:2048
	global_load_dwordx4 v[138:141], v[98:99], off offset:3072
	v_add_co_u32_e32 v98, vcc, s1, v98
	s_nop 1
	v_addc_co_u32_e32 v99, vcc, 0, v99, vcc
	global_load_dwordx4 v[162:165], v[98:99], off
	global_load_dwordx4 v[118:121], v[98:99], off offset:1024
	global_load_dwordx4 v[158:161], v[98:99], off offset:2048
	s_nop 0
	global_load_dwordx4 v[98:101], v[98:99], off offset:3072
.LBB0_1822:
	s_ashr_i32 s23, s22, 31
	s_lshl_b64 s[22:23], s[22:23], 8
	s_add_u32 s1, s22, s39
	s_addc_u32 s15, s23, s44
	s_lshl_b32 s22, s0, 7
	v_lshlrev_b32_e32 v178, 3, v178
	v_or_b32_e32 v188, s1, v179
	s_ashr_i32 s23, s22, 31
	v_ashrrev_i32_e32 v179, 31, v178
	s_waitcnt lgkmcnt(0)
	v_mul_f32_e32 v185, 0xbfb8aa3b, v150
	v_mul_f32_e32 v180, v134, v185
	v_mul_f32_e32 v181, v135, v185
	v_exp_f32_e32 v180, v180
	v_exp_f32_e32 v181, v181
	v_mul_f32_e32 v182, v136, v185
	v_mul_f32_e32 v183, v137, v185
	v_exp_f32_e32 v182, v182
	v_exp_f32_e32 v183, v183
	v_mul_f32_e32 v184, v130, v185
	v_mul_f32_e32 v186, v131, v185
	v_exp_f32_e32 v184, v184
	v_exp_f32_e32 v186, v186
	v_add_f32_e32 v180, 1.0, v180
	v_add_f32_e32 v181, 1.0, v181
	v_mul_f32_e32 v187, v132, v185
	v_mul_f32_e32 v185, v133, v185
	v_rcp_f32_e32 v180, v180
	v_rcp_f32_e32 v181, v181
	v_add_f32_e32 v182, 1.0, v182
	v_add_f32_e32 v183, 1.0, v183
	v_exp_f32_e32 v187, v187
	v_exp_f32_e32 v189, v185
	v_rcp_f32_e32 v182, v182
	v_rcp_f32_e32 v183, v183
	v_add_f32_e32 v184, 1.0, v184
	v_add_f32_e32 v186, 1.0, v186
	v_mul_f32_e32 v150, v150, v150
	v_rcp_f32_e32 v184, v184
	v_rcp_f32_e32 v185, v186
	v_add_f32_e32 v186, 1.0, v187
	v_add_f32_e32 v187, 1.0, v189
	v_pk_mul_f32 v[126:127], v[134:135], v[126:127]
	v_pk_mul_f32 v[134:135], v[150:151], v[180:181] op_sel_hi:[0,1]
	v_rcp_f32_e32 v186, v186
	v_rcp_f32_e32 v187, v187
	v_pk_mul_f32 v[128:129], v[136:137], v[128:129]
	v_pk_mul_f32 v[126:127], v[126:127], v[134:135]
	v_pk_mul_f32 v[134:135], v[150:151], v[182:183] op_sel_hi:[0,1]
	v_pk_mul_f32 v[128:129], v[128:129], v[134:135]
	v_cvt_pk_bf16_f32 v126, v126, v127
	v_cvt_pk_bf16_f32 v127, v128, v129
	v_pk_mul_f32 v[122:123], v[130:131], v[122:123]
	v_pk_mul_f32 v[128:129], v[150:151], v[184:185] op_sel_hi:[0,1]
	v_pk_mul_f32 v[122:123], v[122:123], v[128:129]
	v_pk_mul_f32 v[124:125], v[132:133], v[124:125]
	v_cvt_pk_bf16_f32 v128, v122, v123
	v_pk_mul_f32 v[122:123], v[150:151], v[186:187] op_sel_hi:[0,1]
	v_pk_mul_f32 v[122:123], v[124:125], v[122:123]
	s_movk_i32 s0, 0x1600
	v_cvt_pk_bf16_f32 v129, v122, v123
	v_mov_b64_e32 v[122:123], s[8:9]
	v_mad_u64_u32 v[122:123], s[0:1], v188, s0, v[122:123]
	v_mov_b32_e32 v124, 0x1600
	v_mad_i32_i24 v123, s15, v124, v123
	v_lshl_add_u64 v[122:123], s[22:23], 1, v[122:123]
	v_lshl_add_u64 v[122:123], v[122:123], 0, s[96:97]
	v_lshl_add_u64 v[122:123], v[178:179], 1, v[122:123]
	flat_store_dwordx4 v[122:123], v[126:129]
	v_mul_f32_e32 v125, 0xbfb8aa3b, v151
	v_mul_f32_e32 v124, v114, v125
	v_exp_f32_e32 v126, v124
	v_mul_f32_e32 v124, v115, v125
	v_exp_f32_e32 v127, v124
	v_mul_f32_e32 v128, v116, v125
	v_mul_f32_e32 v129, v117, v125
	v_exp_f32_e32 v128, v128
	v_exp_f32_e32 v129, v129
	v_mul_f32_e32 v130, v110, v125
	v_mul_f32_e32 v131, v111, v125
	v_exp_f32_e32 v130, v130
	v_exp_f32_e32 v131, v131
	v_mul_f32_e32 v132, v112, v125
	v_mul_f32_e32 v125, v113, v125
	v_add_f32_e32 v126, 1.0, v126
	v_add_f32_e32 v127, 1.0, v127
	v_exp_f32_e32 v125, v125
	v_rcp_f32_e32 v126, v126
	v_rcp_f32_e32 v127, v127
	v_add_f32_e32 v128, 1.0, v128
	v_add_f32_e32 v129, 1.0, v129
	v_exp_f32_e32 v132, v132
	v_rcp_f32_e32 v128, v128
	v_rcp_f32_e32 v129, v129
	v_add_f32_e32 v130, 1.0, v130
	v_add_f32_e32 v131, 1.0, v131
	v_mul_f32_e32 v124, v151, v151
	v_rcp_f32_e32 v130, v130
	v_rcp_f32_e32 v131, v131
	v_add_f32_e32 v125, 1.0, v125
	v_add_f32_e32 v132, 1.0, v132
	v_pk_mul_f32 v[106:107], v[114:115], v[106:107]
	v_pk_mul_f32 v[114:115], v[124:125], v[126:127] op_sel_hi:[0,1]
	v_rcp_f32_e32 v132, v132
	v_rcp_f32_e32 v133, v125
	v_pk_mul_f32 v[108:109], v[116:117], v[108:109]
	v_pk_mul_f32 v[106:107], v[106:107], v[114:115]
	v_pk_mul_f32 v[114:115], v[124:125], v[128:129] op_sel_hi:[0,1]
	v_pk_mul_f32 v[108:109], v[108:109], v[114:115]
	v_cvt_pk_bf16_f32 v106, v106, v107
	v_cvt_pk_bf16_f32 v107, v108, v109
	v_pk_mul_f32 v[102:103], v[110:111], v[102:103]
	v_pk_mul_f32 v[108:109], v[124:125], v[130:131] op_sel_hi:[0,1]
	v_pk_mul_f32 v[102:103], v[102:103], v[108:109]
	v_pk_mul_f32 v[104:105], v[112:113], v[104:105]
	v_cvt_pk_bf16_f32 v108, v102, v103
	v_pk_mul_f32 v[102:103], v[124:125], v[132:133] op_sel_hi:[0,1]
	v_pk_mul_f32 v[102:103], v[104:105], v[102:103]
	s_mov_b32 s0, 0x16000
; DI u32x4 pk8(f32x4 a, f32x4 b) { u32x4 o; o.x = pk2(a.x, a.y); o.y = pk2(a.z, a.w); o.z = pk2(b.x, b.y); o.w = pk2(b.z, b.w); return o; }
; DI float fexp2(float x) { return __builtin_amdgcn_exp2f(x); }
; DI float frcp(float x) { return __builtin_amdgcn_rcpf(x); }
; #define EPI_SCHED() __builtin_amdgcn_sched_barrier(0)
;     DI void operator()(const AccT& acc, const Unit& u, const Unit& nxt, bool has_next, int wr, int wc, int fr, int fq, float (&rs_unused)[2][4]) const {
;     ...
; #pragma unroll
;         for (int ai = 0; ai < 2; ++ai)
; #pragma unroll
;             for (int m = 0; m < 4; ++m) {
;                 EPI_SCHED(); const size_t row = row0 + ai * 128 + m * 16;
;                 f32x4 o[2];
;                 const float c1 = -LOG2E * rs[ai][m], rs2 = rs[ai][m] * rs[ai][m];
; #pragma unroll
;                 for (int n = 0; n < 2; ++n) {
;                     const f32x4 gt = acc[ai][0][m][n], t = gt * acc[ai][1][m][n];
; #pragma unroll
;                     for (int e = 0; e < 4; ++e) o[n][e] = t[e] * (rs2 * frcp(1.f + fexp2(gt[e] * c1)));
;                 }
;                 *(u32x4*)(hid + row * FF + u.pn * 128 + wc * 32 + fq * 8) = pk8(o[0], o[1]);
	v_cvt_pk_bf16_f32 v109, v102, v103
	v_add_co_u32_e32 v102, vcc, s0, v122
	s_nop 1
	v_addc_co_u32_e32 v103, vcc, 0, v123, vcc
	flat_store_dwordx4 v[102:103], v[106:109]
	v_mul_f32_e32 v103, 0xbfb8aa3b, v152
	v_mul_f32_e32 v102, v94, v103
	v_exp_f32_e32 v104, v102
	v_mul_f32_e32 v102, v95, v103
	v_exp_f32_e32 v105, v102
	v_mul_f32_e32 v106, v96, v103
	v_mul_f32_e32 v107, v97, v103
	v_exp_f32_e32 v106, v106
	v_exp_f32_e32 v107, v107
	v_mul_f32_e32 v108, v90, v103
	v_mul_f32_e32 v109, v91, v103
	v_exp_f32_e32 v108, v108
	v_exp_f32_e32 v109, v109
	v_mul_f32_e32 v110, v92, v103
	v_mul_f32_e32 v103, v93, v103
	v_add_f32_e32 v104, 1.0, v104
	v_add_f32_e32 v105, 1.0, v105
	v_exp_f32_e32 v103, v103
	v_rcp_f32_e32 v104, v104
	v_rcp_f32_e32 v105, v105
	v_add_f32_e32 v106, 1.0, v106
	v_add_f32_e32 v107, 1.0, v107
	v_exp_f32_e32 v110, v110
	v_rcp_f32_e32 v106, v106
	v_rcp_f32_e32 v107, v107
	v_add_f32_e32 v108, 1.0, v108
	v_add_f32_e32 v109, 1.0, v109
	v_mul_f32_e32 v102, v152, v152
	v_rcp_f32_e32 v108, v108
	v_rcp_f32_e32 v109, v109
	v_add_f32_e32 v103, 1.0, v103
	v_add_f32_e32 v110, 1.0, v110
	v_pk_mul_f32 v[86:87], v[94:95], v[86:87]
	v_pk_mul_f32 v[94:95], v[102:103], v[104:105] op_sel_hi:[0,1]
	v_rcp_f32_e32 v110, v110
	v_rcp_f32_e32 v111, v103
	v_pk_mul_f32 v[88:89], v[96:97], v[88:89]
	v_pk_mul_f32 v[86:87], v[86:87], v[94:95]
	v_pk_mul_f32 v[94:95], v[102:103], v[106:107] op_sel_hi:[0,1]
	v_pk_mul_f32 v[88:89], v[88:89], v[94:95]
	v_cvt_pk_bf16_f32 v86, v86, v87
	v_cvt_pk_bf16_f32 v87, v88, v89
	v_pk_mul_f32 v[82:83], v[90:91], v[82:83]
	v_pk_mul_f32 v[88:89], v[102:103], v[108:109] op_sel_hi:[0,1]
	v_pk_mul_f32 v[82:83], v[82:83], v[88:89]
	v_pk_mul_f32 v[84:85], v[92:93], v[84:85]
	v_cvt_pk_bf16_f32 v88, v82, v83
	v_pk_mul_f32 v[82:83], v[102:103], v[110:111] op_sel_hi:[0,1]
	v_pk_mul_f32 v[82:83], v[84:85], v[82:83]
	s_mov_b32 s0, 0x2c000
	v_cvt_pk_bf16_f32 v89, v82, v83
	v_add_co_u32_e32 v82, vcc, s0, v122
	s_nop 1
	v_addc_co_u32_e32 v83, vcc, 0, v123, vcc
	flat_store_dwordx4 v[82:83], v[86:89]
	v_mul_f32_e32 v83, 0xbfb8aa3b, v153
	v_mul_f32_e32 v82, v78, v83
	v_exp_f32_e32 v84, v82
	v_mul_f32_e32 v82, v79, v83
	v_exp_f32_e32 v85, v82
	v_mul_f32_e32 v86, v80, v83
	v_mul_f32_e32 v87, v81, v83
	v_exp_f32_e32 v86, v86
	v_exp_f32_e32 v87, v87
	v_mul_f32_e32 v88, v74, v83
	v_mul_f32_e32 v89, v75, v83
	v_exp_f32_e32 v88, v88
	v_exp_f32_e32 v89, v89
	v_mul_f32_e32 v90, v76, v83
	v_mul_f32_e32 v83, v77, v83
	v_add_f32_e32 v84, 1.0, v84
	v_add_f32_e32 v85, 1.0, v85
	v_exp_f32_e32 v83, v83
	v_rcp_f32_e32 v84, v84
	v_rcp_f32_e32 v85, v85
	v_add_f32_e32 v86, 1.0, v86
	v_add_f32_e32 v87, 1.0, v87
	v_exp_f32_e32 v90, v90
	v_rcp_f32_e32 v86, v86
	v_rcp_f32_e32 v87, v87
	v_add_f32_e32 v88, 1.0, v88
	v_add_f32_e32 v89, 1.0, v89
	v_mul_f32_e32 v82, v153, v153
	v_rcp_f32_e32 v88, v88
	v_rcp_f32_e32 v89, v89
	v_add_f32_e32 v83, 1.0, v83
	v_add_f32_e32 v90, 1.0, v90
	v_pk_mul_f32 v[70:71], v[78:79], v[70:71]
	v_pk_mul_f32 v[78:79], v[82:83], v[84:85] op_sel_hi:[0,1]
	v_rcp_f32_e32 v90, v90
	v_rcp_f32_e32 v91, v83
	v_pk_mul_f32 v[72:73], v[80:81], v[72:73]
	v_pk_mul_f32 v[70:71], v[70:71], v[78:79]
	v_pk_mul_f32 v[78:79], v[82:83], v[86:87] op_sel_hi:[0,1]
	v_pk_mul_f32 v[72:73], v[72:73], v[78:79]
	v_cvt_pk_bf16_f32 v70, v70, v71
	v_cvt_pk_bf16_f32 v71, v72, v73
	v_pk_mul_f32 v[66:67], v[74:75], v[66:67]
	v_pk_mul_f32 v[72:73], v[82:83], v[88:89] op_sel_hi:[0,1]
	v_pk_mul_f32 v[66:67], v[66:67], v[72:73]
	v_pk_mul_f32 v[68:69], v[76:77], v[68:69]
	v_cvt_pk_bf16_f32 v72, v66, v67
	v_pk_mul_f32 v[66:67], v[82:83], v[90:91] op_sel_hi:[0,1]
	v_pk_mul_f32 v[66:67], v[68:69], v[66:67]
	s_mov_b32 s0, 0x42000
	v_cvt_pk_bf16_f32 v73, v66, v67
	v_add_co_u32_e32 v66, vcc, s0, v122
	s_nop 1
	v_addc_co_u32_e32 v67, vcc, 0, v123, vcc
	flat_store_dwordx4 v[66:67], v[70:73]
	v_mul_f32_e32 v67, 0xbfb8aa3b, v146
	v_mul_f32_e32 v66, v62, v67
	v_exp_f32_e32 v68, v66
	v_mul_f32_e32 v66, v63, v67
	v_exp_f32_e32 v69, v66
	v_mul_f32_e32 v70, v64, v67
	v_mul_f32_e32 v71, v65, v67
	v_exp_f32_e32 v70, v70
	v_exp_f32_e32 v71, v71
	v_mul_f32_e32 v72, v58, v67
	v_mul_f32_e32 v73, v59, v67
	v_exp_f32_e32 v72, v72
	v_exp_f32_e32 v73, v73
	v_mul_f32_e32 v74, v60, v67
	v_mul_f32_e32 v67, v61, v67
	v_add_f32_e32 v68, 1.0, v68
	v_add_f32_e32 v69, 1.0, v69
	v_exp_f32_e32 v67, v67
	v_rcp_f32_e32 v68, v68
	v_rcp_f32_e32 v69, v69
	v_add_f32_e32 v70, 1.0, v70
	v_add_f32_e32 v71, 1.0, v71
	v_exp_f32_e32 v74, v74
	v_rcp_f32_e32 v70, v70
	v_rcp_f32_e32 v71, v71
	v_add_f32_e32 v72, 1.0, v72
	v_add_f32_e32 v73, 1.0, v73
	v_mul_f32_e32 v66, v146, v146
	v_rcp_f32_e32 v72, v72
	v_rcp_f32_e32 v73, v73
	v_add_f32_e32 v67, 1.0, v67
	v_add_f32_e32 v74, 1.0, v74
	v_pk_mul_f32 v[54:55], v[62:63], v[54:55]
	v_pk_mul_f32 v[62:63], v[66:67], v[68:69] op_sel_hi:[0,1]
	v_rcp_f32_e32 v74, v74
	v_rcp_f32_e32 v75, v67
	v_pk_mul_f32 v[56:57], v[64:65], v[56:57]
	v_pk_mul_f32 v[54:55], v[54:55], v[62:63]
	v_pk_mul_f32 v[62:63], v[66:67], v[70:71] op_sel_hi:[0,1]
	v_pk_mul_f32 v[56:57], v[56:57], v[62:63]
	v_cvt_pk_bf16_f32 v54, v54, v55
	v_cvt_pk_bf16_f32 v55, v56, v57
	v_pk_mul_f32 v[50:51], v[58:59], v[50:51]
	v_pk_mul_f32 v[56:57], v[66:67], v[72:73] op_sel_hi:[0,1]
	v_pk_mul_f32 v[50:51], v[50:51], v[56:57]
	v_pk_mul_f32 v[52:53], v[60:61], v[52:53]
	v_cvt_pk_bf16_f32 v56, v50, v51
	v_pk_mul_f32 v[50:51], v[66:67], v[74:75] op_sel_hi:[0,1]
	v_pk_mul_f32 v[50:51], v[52:53], v[50:51]
	s_mov_b32 s0, 0xb0000
	v_cvt_pk_bf16_f32 v57, v50, v51
	v_add_co_u32_e32 v50, vcc, s0, v122
	s_nop 1
	v_addc_co_u32_e32 v51, vcc, 0, v123, vcc
	flat_store_dwordx4 v[50:51], v[54:57]
	v_mul_f32_e32 v51, 0xbfb8aa3b, v147
	v_mul_f32_e32 v50, v46, v51
; DI u32x4 pk8(f32x4 a, f32x4 b) { u32x4 o; o.x = pk2(a.x, a.y); o.y = pk2(a.z, a.w); o.z = pk2(b.x, b.y); o.w = pk2(b.z, b.w); return o; }
; DI float fexp2(float x) { return __builtin_amdgcn_exp2f(x); }
; DI float frcp(float x) { return __builtin_amdgcn_rcpf(x); }
; #define EPI_SCHED() __builtin_amdgcn_sched_barrier(0)
;     DI void operator()(const AccT& acc, const Unit& u, const Unit& nxt, bool has_next, int wr, int wc, int fr, int fq, float (&rs_unused)[2][4]) const {
;     ...
; #pragma unroll
;         for (int ai = 0; ai < 2; ++ai)
; #pragma unroll
;             for (int m = 0; m < 4; ++m) {
;                 EPI_SCHED(); const size_t row = row0 + ai * 128 + m * 16;
;                 f32x4 o[2];
;                 const float c1 = -LOG2E * rs[ai][m], rs2 = rs[ai][m] * rs[ai][m];
; #pragma unroll
;                 for (int n = 0; n < 2; ++n) {
;                     const f32x4 gt = acc[ai][0][m][n], t = gt * acc[ai][1][m][n];
; #pragma unroll
;                     for (int e = 0; e < 4; ++e) o[n][e] = t[e] * (rs2 * frcp(1.f + fexp2(gt[e] * c1)));
;                 }
;                 *(u32x4*)(hid + row * FF + u.pn * 128 + wc * 32 + fq * 8) = pk8(o[0], o[1]);
	v_exp_f32_e32 v52, v50
	v_mul_f32_e32 v50, v47, v51
	v_exp_f32_e32 v53, v50
	v_mul_f32_e32 v54, v48, v51
	v_mul_f32_e32 v55, v49, v51
	v_exp_f32_e32 v54, v54
	v_exp_f32_e32 v55, v55
	v_mul_f32_e32 v56, v42, v51
	v_mul_f32_e32 v57, v43, v51
	v_exp_f32_e32 v56, v56
	v_exp_f32_e32 v57, v57
	v_mul_f32_e32 v58, v44, v51
	v_mul_f32_e32 v51, v45, v51
	v_add_f32_e32 v52, 1.0, v52
	v_add_f32_e32 v53, 1.0, v53
	v_exp_f32_e32 v51, v51
	v_rcp_f32_e32 v52, v52
	v_rcp_f32_e32 v53, v53
	v_add_f32_e32 v54, 1.0, v54
	v_add_f32_e32 v55, 1.0, v55
	v_exp_f32_e32 v58, v58
	v_rcp_f32_e32 v54, v54
	v_rcp_f32_e32 v55, v55
	v_add_f32_e32 v56, 1.0, v56
	v_add_f32_e32 v57, 1.0, v57
	v_mul_f32_e32 v50, v147, v147
	v_rcp_f32_e32 v56, v56
	v_rcp_f32_e32 v57, v57
	v_add_f32_e32 v51, 1.0, v51
	v_add_f32_e32 v58, 1.0, v58
	v_pk_mul_f32 v[38:39], v[46:47], v[38:39]
	v_pk_mul_f32 v[46:47], v[50:51], v[52:53] op_sel_hi:[0,1]
	v_rcp_f32_e32 v58, v58
	v_rcp_f32_e32 v59, v51
	v_pk_mul_f32 v[40:41], v[48:49], v[40:41]
	v_pk_mul_f32 v[38:39], v[38:39], v[46:47]
	v_pk_mul_f32 v[46:47], v[50:51], v[54:55] op_sel_hi:[0,1]
	v_pk_mul_f32 v[40:41], v[40:41], v[46:47]
	v_cvt_pk_bf16_f32 v38, v38, v39
	v_cvt_pk_bf16_f32 v39, v40, v41
	v_pk_mul_f32 v[34:35], v[42:43], v[34:35]
	v_pk_mul_f32 v[40:41], v[50:51], v[56:57] op_sel_hi:[0,1]
	v_pk_mul_f32 v[34:35], v[34:35], v[40:41]
	v_pk_mul_f32 v[36:37], v[44:45], v[36:37]
	v_cvt_pk_bf16_f32 v40, v34, v35
	v_pk_mul_f32 v[34:35], v[50:51], v[58:59] op_sel_hi:[0,1]
	v_pk_mul_f32 v[34:35], v[36:37], v[34:35]
	s_mov_b32 s0, 0xc6000
	v_cvt_pk_bf16_f32 v41, v34, v35
	v_add_co_u32_e32 v34, vcc, s0, v122
	s_nop 1
	v_addc_co_u32_e32 v35, vcc, 0, v123, vcc
	flat_store_dwordx4 v[34:35], v[38:41]
	v_mul_f32_e32 v35, 0xbfb8aa3b, v148
	v_mul_f32_e32 v34, v30, v35
	v_exp_f32_e32 v36, v34
	v_mul_f32_e32 v34, v31, v35
	v_exp_f32_e32 v37, v34
	v_mul_f32_e32 v38, v32, v35
	v_mul_f32_e32 v39, v33, v35
	v_exp_f32_e32 v38, v38
	v_exp_f32_e32 v39, v39
	v_mul_f32_e32 v40, v26, v35
	v_mul_f32_e32 v41, v27, v35
	v_exp_f32_e32 v40, v40
	v_exp_f32_e32 v41, v41
	v_mul_f32_e32 v42, v28, v35
	v_mul_f32_e32 v35, v29, v35
	v_add_f32_e32 v36, 1.0, v36
	v_add_f32_e32 v37, 1.0, v37
	v_exp_f32_e32 v35, v35
	v_rcp_f32_e32 v36, v36
	v_rcp_f32_e32 v37, v37
	v_add_f32_e32 v38, 1.0, v38
	v_add_f32_e32 v39, 1.0, v39
	v_exp_f32_e32 v42, v42
	v_rcp_f32_e32 v38, v38
	v_rcp_f32_e32 v39, v39
	v_add_f32_e32 v40, 1.0, v40
	v_add_f32_e32 v41, 1.0, v41
	v_mul_f32_e32 v34, v148, v148
	v_rcp_f32_e32 v40, v40
	v_rcp_f32_e32 v41, v41
	v_add_f32_e32 v35, 1.0, v35
	v_add_f32_e32 v42, 1.0, v42
	v_pk_mul_f32 v[22:23], v[30:31], v[22:23]
	v_pk_mul_f32 v[30:31], v[34:35], v[36:37] op_sel_hi:[0,1]
	v_rcp_f32_e32 v42, v42
	v_rcp_f32_e32 v43, v35
	v_pk_mul_f32 v[24:25], v[32:33], v[24:25]
	v_pk_mul_f32 v[22:23], v[22:23], v[30:31]
	v_pk_mul_f32 v[30:31], v[34:35], v[38:39] op_sel_hi:[0,1]
	v_pk_mul_f32 v[24:25], v[24:25], v[30:31]
	v_cvt_pk_bf16_f32 v22, v22, v23
	v_cvt_pk_bf16_f32 v23, v24, v25
	v_pk_mul_f32 v[18:19], v[26:27], v[18:19]
	v_pk_mul_f32 v[24:25], v[34:35], v[40:41] op_sel_hi:[0,1]
	v_pk_mul_f32 v[18:19], v[18:19], v[24:25]
	v_pk_mul_f32 v[20:21], v[28:29], v[20:21]
	v_cvt_pk_bf16_f32 v24, v18, v19
	v_pk_mul_f32 v[18:19], v[34:35], v[42:43] op_sel_hi:[0,1]
	v_pk_mul_f32 v[18:19], v[20:21], v[18:19]
	s_mov_b32 s0, 0xdc000
	v_cvt_pk_bf16_f32 v25, v18, v19
	v_add_co_u32_e32 v18, vcc, s0, v122
	s_nop 1
	v_addc_co_u32_e32 v19, vcc, 0, v123, vcc
	flat_store_dwordx4 v[18:19], v[22:25]
	v_mul_f32_e32 v19, 0xbfb8aa3b, v149
	v_mul_f32_e32 v18, v14, v19
	v_exp_f32_e32 v20, v18
	v_mul_f32_e32 v18, v15, v19
	v_exp_f32_e32 v21, v18
	v_mul_f32_e32 v22, v16, v19
	v_mul_f32_e32 v23, v17, v19
	v_exp_f32_e32 v22, v22
	v_exp_f32_e32 v23, v23
	v_mul_f32_e32 v24, v10, v19
	v_mul_f32_e32 v25, v11, v19
	v_exp_f32_e32 v24, v24
	v_exp_f32_e32 v25, v25
	v_mul_f32_e32 v26, v12, v19
	v_mul_f32_e32 v19, v13, v19
	v_add_f32_e32 v20, 1.0, v20
	v_add_f32_e32 v21, 1.0, v21
	v_exp_f32_e32 v19, v19
	v_rcp_f32_e32 v20, v20
	v_rcp_f32_e32 v21, v21
	v_add_f32_e32 v22, 1.0, v22
	v_add_f32_e32 v23, 1.0, v23
	v_exp_f32_e32 v26, v26
	v_rcp_f32_e32 v22, v22
	v_rcp_f32_e32 v23, v23
	v_add_f32_e32 v24, 1.0, v24
	v_add_f32_e32 v25, 1.0, v25
	v_mul_f32_e32 v18, v149, v149
	v_rcp_f32_e32 v24, v24
	v_rcp_f32_e32 v25, v25
	v_add_f32_e32 v19, 1.0, v19
	v_add_f32_e32 v26, 1.0, v26
	v_pk_mul_f32 v[6:7], v[14:15], v[6:7]
	v_pk_mul_f32 v[14:15], v[18:19], v[20:21] op_sel_hi:[0,1]
	v_rcp_f32_e32 v26, v26
	v_rcp_f32_e32 v27, v19
	v_pk_mul_f32 v[8:9], v[16:17], v[8:9]
	v_pk_mul_f32 v[6:7], v[6:7], v[14:15]
	v_pk_mul_f32 v[14:15], v[18:19], v[22:23] op_sel_hi:[0,1]
	v_pk_mul_f32 v[8:9], v[8:9], v[14:15]
	v_cvt_pk_bf16_f32 v6, v6, v7
	v_cvt_pk_bf16_f32 v7, v8, v9
	v_pk_mul_f32 v[2:3], v[10:11], v[2:3]
	v_pk_mul_f32 v[8:9], v[18:19], v[24:25] op_sel_hi:[0,1]
	v_pk_mul_f32 v[2:3], v[2:3], v[8:9]
	v_pk_mul_f32 v[4:5], v[12:13], v[4:5]
	v_cvt_pk_bf16_f32 v8, v2, v3
	v_pk_mul_f32 v[2:3], v[18:19], v[26:27] op_sel_hi:[0,1]
	v_pk_mul_f32 v[2:3], v[4:5], v[2:3]
	s_nop 0
	v_cvt_pk_bf16_f32 v9, v2, v3
	v_add_co_u32_e32 v2, vcc, 0xf2000, v122
	s_nop 1
	v_addc_co_u32_e32 v3, vcc, 0, v123, vcc
	s_and_b64 vcc, exec, s[2:3]
	s_mov_b64 s[2:3], -1
	flat_store_dwordx4 v[2:3], v[6:9]
	s_cbranch_vccnz .LBB0_1813
;     DI static void park(const float (&rs)[2][4], int t) { LAS f32x4* p = slot(t); p[0] = (f32x4){rs[0][0], rs[0][1], rs[0][2], rs[0][3]}; p[1] = (f32x4){rs[1][0], rs[1][1], rs[1][2], rs[1][3]}; }
;     DI void operator()(const AccT& acc, const Unit& u, const Unit& nxt, bool has_next, int wr, int wc, int fr, int fq, float (&rs_unused)[2][4]) const {
;     ...
;         if (has_next) {
; #pragma unroll
;             for (int ai = 0; ai < 2; ++ai)
; #pragma unroll
;                 for (int m = 0; m < 4; ++m) {
;                     float t = (nv[ai][m].x + nv[ai][m].y) + (nv[ai][m].z + nv[ai][m].w);
;                     t += __shfl_xor(t, 16); t += __shfl_xor(t, 32);
;                     rs[ai][m] = rsqrtf(t * (1.f / 1024.f) + EPS);
;                 }
;             park(rs, myt);
	s_waitcnt vmcnt(8)
	v_mov_b32_e32 v2, v154
	v_mov_b32_e32 v3, v155
	v_mov_b32_e32 v4, v156
	v_mov_b32_e32 v5, v157
	v_mov_b32_e32 v156, v158
	v_mov_b32_e32 v157, v98
	v_mov_b32_e32 v155, v100
	v_mov_b32_e32 v98, v159
	v_mov_b32_e32 v154, v160
	v_mov_b32_e32 v100, v161
	v_mov_b32_e32 v161, v118
	v_mov_b32_e32 v159, v120
	v_mov_b32_e32 v160, v162
	v_mov_b32_e32 v118, v163
	v_mov_b32_e32 v158, v164
	v_mov_b32_e32 v120, v165
	v_mov_b32_e32 v165, v138
	v_mov_b32_e32 v163, v140
	v_mov_b32_e32 v164, v166
	v_mov_b32_e32 v138, v167
	v_mov_b32_e32 v162, v168
	v_mov_b32_e32 v140, v169
	v_mov_b32_e32 v169, v142
	v_mov_b32_e32 v167, v144
	v_mov_b32_e32 v168, v2
	v_mov_b32_e32 v142, v3
	v_mov_b32_e32 v166, v4
	v_mov_b32_e32 v144, v5
	v_pk_add_f32 v[2:3], v[168:169], v[142:143]
	v_pk_add_f32 v[4:5], v[166:167], v[144:145]
	s_mov_b32 s0, 0x358637bd
	v_pk_add_f32 v[2:3], v[2:3], v[4:5]
	ds_bpermute_b32 v4, v174, v2
	ds_bpermute_b32 v5, v174, v3
	v_mov_b64_e32 v[6:7], s[0:1]
	v_pk_add_f32 v[8:9], v[162:163], v[140:141]
	v_pk_add_f32 v[10:11], v[158:159], v[120:121]
	v_pk_add_f32 v[12:13], v[154:155], v[100:101]
	s_waitcnt lgkmcnt(0)
	v_pk_add_f32 v[2:3], v[2:3], v[4:5]
	ds_bpermute_b32 v4, v175, v2
	ds_bpermute_b32 v5, v175, v3
	s_waitcnt lgkmcnt(0)
	v_pk_add_f32 v[2:3], v[2:3], v[4:5]
	s_nop 0
	v_pk_fma_f32 v[2:3], v[2:3], s[88:89], v[6:7] op_sel_hi:[1,0,0]
	s_nop 0
	v_mul_f32_e32 v4, 0x4b800000, v2
	v_cmp_gt_f32_e64 s[2:3], s42, v2
	v_cmp_gt_f32_e32 vcc, s42, v3
	s_nop 0
	v_cndmask_b32_e64 v2, v2, v4, s[2:3]
	v_mul_f32_e32 v4, 0x4b800000, v3
	v_cndmask_b32_e32 v3, v3, v4, vcc
	v_rsq_f32_e32 v2, v2
	v_rsq_f32_e32 v3, v3
	s_nop 0
	v_pk_mul_f32 v[4:5], v[2:3], s[52:53] op_sel_hi:[1,0]
	s_nop 0
	v_cndmask_b32_e32 v3, v3, v5, vcc
	v_cndmask_b32_e64 v2, v2, v4, s[2:3]
	v_pk_add_f32 v[4:5], v[164:165], v[138:139]
	s_nop 0
	v_pk_add_f32 v[4:5], v[4:5], v[8:9]
	ds_bpermute_b32 v8, v174, v4
	ds_bpermute_b32 v9, v174, v5
	s_waitcnt lgkmcnt(0)
	v_pk_add_f32 v[4:5], v[4:5], v[8:9]
	ds_bpermute_b32 v8, v175, v4
	ds_bpermute_b32 v9, v175, v5
	s_waitcnt lgkmcnt(0)
	v_pk_add_f32 v[4:5], v[4:5], v[8:9]
	s_nop 0
	v_pk_fma_f32 v[4:5], v[4:5], s[88:89], v[6:7] op_sel_hi:[1,0,0]
	s_nop 0
	v_mul_f32_e32 v8, 0x4b800000, v4
	v_cmp_gt_f32_e64 s[2:3], s42, v4
	v_cmp_gt_f32_e32 vcc, s42, v5
	s_nop 0
	v_cndmask_b32_e64 v4, v4, v8, s[2:3]
	v_mul_f32_e32 v8, 0x4b800000, v5
	v_cndmask_b32_e32 v5, v5, v8, vcc
	v_rsq_f32_e32 v4, v4
	v_rsq_f32_e32 v5, v5
	s_nop 0
	v_pk_mul_f32 v[8:9], v[4:5], s[52:53] op_sel_hi:[1,0]
	s_nop 0
	v_cndmask_b32_e32 v5, v5, v9, vcc
	v_cndmask_b32_e64 v4, v4, v8, s[2:3]
	v_pk_add_f32 v[8:9], v[160:161], v[118:119]
	s_nop 0
	v_pk_add_f32 v[8:9], v[8:9], v[10:11]
	ds_bpermute_b32 v10, v174, v8
	ds_bpermute_b32 v11, v174, v9
	s_waitcnt lgkmcnt(0)
	v_pk_add_f32 v[8:9], v[8:9], v[10:11]
	ds_bpermute_b32 v10, v175, v8
	ds_bpermute_b32 v11, v175, v9
	s_waitcnt lgkmcnt(0)
	v_pk_add_f32 v[8:9], v[8:9], v[10:11]
	s_nop 0
	v_pk_fma_f32 v[8:9], v[8:9], s[88:89], v[6:7] op_sel_hi:[1,0,0]
	s_nop 0
	v_mul_f32_e32 v10, 0x4b800000, v8
	v_cmp_gt_f32_e64 s[2:3], s42, v8
	v_cmp_gt_f32_e32 vcc, s42, v9
	s_nop 0
	v_cndmask_b32_e64 v8, v8, v10, s[2:3]
	v_mul_f32_e32 v10, 0x4b800000, v9
	v_cndmask_b32_e32 v9, v9, v10, vcc
	v_rsq_f32_e32 v8, v8
	v_rsq_f32_e32 v9, v9
	s_nop 0
	v_pk_mul_f32 v[10:11], v[8:9], s[52:53] op_sel_hi:[1,0]
	s_nop 0
	v_cndmask_b32_e32 v9, v9, v11, vcc
	v_cndmask_b32_e64 v8, v8, v10, s[2:3]
	v_pk_add_f32 v[10:11], v[156:157], v[98:99]
	s_nop 0
	v_pk_add_f32 v[10:11], v[10:11], v[12:13]
	ds_bpermute_b32 v12, v174, v10
	ds_bpermute_b32 v13, v174, v11
	s_waitcnt lgkmcnt(0)
	v_pk_add_f32 v[10:11], v[10:11], v[12:13]
	ds_bpermute_b32 v12, v175, v10
	ds_bpermute_b32 v13, v175, v11
	s_waitcnt lgkmcnt(0)
	v_pk_add_f32 v[10:11], v[10:11], v[12:13]
	s_nop 0
	v_pk_fma_f32 v[6:7], v[10:11], s[88:89], v[6:7] op_sel_hi:[1,0,0]
	s_nop 0
	v_mul_f32_e32 v10, 0x4b800000, v6
	v_cmp_gt_f32_e64 s[2:3], s42, v6
	v_cmp_gt_f32_e32 vcc, s42, v7
	s_nop 0
	v_cndmask_b32_e64 v6, v6, v10, s[2:3]
	v_mul_f32_e32 v10, 0x4b800000, v7
	v_cndmask_b32_e32 v7, v7, v10, vcc
	v_rsq_f32_e32 v6, v6
	v_rsq_f32_e32 v7, v7
	s_nop 0
	v_pk_mul_f32 v[10:11], v[6:7], s[52:53] op_sel_hi:[1,0]
	s_nop 0
	v_cndmask_b32_e32 v11, v7, v11, vcc
	s_andn2_b64 vcc, exec, s[6:7]
	v_cndmask_b32_e64 v10, v6, v10, s[2:3]
	ds_write_b128 v177, v[2:5]
	ds_write_b128 v177, v[8:11] offset:16
	s_cbranch_vccnz .LBB0_1812
	s_barrier
	s_branch .LBB0_1812
